# phase-8 w_down bf16 copy (first read in phase 13): nt hint on its stores so the lines are not left dirty in L2 for the barrier write-back
# baseline (speedup 1.0000x reference)
; #define LAS __attribute__((address_space(3)))
; __device__ __forceinline__ unsigned pk2(float lo, float hi) { return pg8::cvt_pk_bf16(lo, hi); }
; #define LDS_WAIT() asm volatile("s_waitcnt lgkmcnt(0)" ::: "memory")
; __device__ __forceinline__ void tr_item(const float* W, int N, int scol0, int valid, const float* gain, bf16_t* WT, int K, int drow0, LAS float* scr, int kb, int lane) {
;     const int k0 = 64 * kb, rr = lane >> 3, c4 = (lane & 7) * 4;
;     f32x4 tv[8];
; #pragma unroll
;     for (int i = 0; i < 8; ++i) tv[i] = (c4 < valid) ? __builtin_nontemporal_load((const f32x4*)(W + (size_t)(k0 + 8 * i + rr) * N + scol0 + c4)) : (f32x4){0.f, 0.f, 0.f, 0.f};
; #pragma unroll
;     for (int i = 0; i < 8; ++i) { const int kk = 8 * i + rr; const float g = gain ? gain[k0 + kk] : 1.f;
;         scr[kk * 33 + c4] = tv[i][0] * g; scr[kk * 33 + c4 + 1] = tv[i][1] * g; scr[kk * 33 + c4 + 2] = tv[i][2] * g; scr[kk * 33 + c4 + 3] = tv[i][3] * g; }
;     LDS_WAIT(); asm volatile("" ::: "memory");
;     const int c = lane & 7;
; #pragma unroll
;     for (int j = 0; j < 4; ++j) { const int nn = (lane >> 3) + 8 * j; const LAS float* s = scr + (8 * c) * 33 + nn;
;         u32x4 o; o.x = pk2(s[0 * 33], s[1 * 33]); o.y = pk2(s[2 * 33], s[3 * 33]); o.z = pk2(s[4 * 33], s[5 * 33]); o.w = pk2(s[6 * 33], s[7 * 33]);
;         *(u32x4*)(WT + (size_t)(drow0 + nn) * K + k0 + 8 * c) = o; }
;     LDS_WAIT(); asm volatile("" ::: "memory");
; __global__ void __launch_bounds__(512, 2) mk_fwd(Args a_) {
;     ...
; #pragma nounroll
;             for (int it = gw; it < 5632; it += NGW) tr_mat_item(a, 11, it, scr, lane);
.LBB0_738:
	s_ashr_i32 s7, s4, 31
	s_lshr_b32 s7, s7, 26
	s_add_i32 s9, s4, s7
	s_ashr_i32 s7, s9, 6
	s_lshl_b32 s8, s7, 11
	s_and_b32 s12, s9, 0xffffffc0
	s_sub_i32 s8, s5, s8
	v_or_b32_e32 v40, s12, v24
	s_ashr_i32 s9, s8, 31
	v_ashrrev_i32_e32 v41, 31, v40
	v_or_b32_e32 v6, 8, v40
	v_lshl_add_u64 v[22:23], s[8:9], 2, v[18:19]
	v_lshlrev_b64 v[2:3], 13, v[40:41]
	v_ashrrev_i32_e32 v7, 31, v6
	v_lshl_add_u64 v[2:3], v[22:23], 0, v[2:3]
	v_lshlrev_b64 v[6:7], 13, v[6:7]
	v_or_b32_e32 v10, 16, v40
	global_load_dwordx4 v[2:5], v[2:3], off nt
	v_lshl_add_u64 v[6:7], v[22:23], 0, v[6:7]
	v_ashrrev_i32_e32 v11, 31, v10
	global_load_dwordx4 v[6:9], v[6:7], off nt
	v_lshlrev_b64 v[10:11], 13, v[10:11]
	v_or_b32_e32 v14, 24, v40
	v_lshl_add_u64 v[10:11], v[22:23], 0, v[10:11]
	v_ashrrev_i32_e32 v15, 31, v14
	global_load_dwordx4 v[10:13], v[10:11], off nt
	v_lshlrev_b64 v[14:15], 13, v[14:15]
	v_or_b32_e32 v28, 32, v40
	v_lshl_add_u64 v[14:15], v[22:23], 0, v[14:15]
	v_ashrrev_i32_e32 v29, 31, v28
	global_load_dwordx4 v[14:17], v[14:15], off nt
	v_lshlrev_b64 v[28:29], 13, v[28:29]
	v_or_b32_e32 v32, 40, v40
	v_lshl_add_u64 v[28:29], v[22:23], 0, v[28:29]
	v_ashrrev_i32_e32 v33, 31, v32
	global_load_dwordx4 v[28:31], v[28:29], off nt
	v_lshlrev_b64 v[32:33], 13, v[32:33]
	v_or_b32_e32 v36, 48, v40
	v_lshl_add_u64 v[32:33], v[22:23], 0, v[32:33]
	v_ashrrev_i32_e32 v37, 31, v36
	global_load_dwordx4 v[32:35], v[32:33], off nt
	v_lshlrev_b64 v[36:37], 13, v[36:37]
	v_or_b32_e32 v40, 56, v40
	v_lshl_add_u64 v[36:37], v[22:23], 0, v[36:37]
	v_ashrrev_i32_e32 v41, 31, v40
	global_load_dwordx4 v[36:39], v[36:37], off nt
	v_lshlrev_b64 v[40:41], 13, v[40:41]
	v_lshl_add_u64 v[22:23], v[22:23], 0, v[40:41]
	global_load_dwordx4 v[40:43], v[22:23], off nt
	s_mul_i32 s7, s7, 0xff500000
	s_ashr_i32 s13, s12, 31
	s_add_i32 s4, s4, s60
	s_add_i32 s5, s5, s6
	s_cmpk_gt_i32 s4, 0x15ff
	s_waitcnt vmcnt(7)
	ds_write2_b32 v26, v2, v3 offset1:1
	ds_write2_b32 v26, v4, v5 offset0:2 offset1:3
	v_add_u32_e32 v2, 0x420, v26
	s_waitcnt vmcnt(6)
	ds_write2_b32 v2, v6, v7 offset1:1
	v_add_u32_e32 v2, 0x428, v26
	ds_write2_b32 v2, v8, v9 offset1:1
	v_add_u32_e32 v2, 0x840, v26
	s_waitcnt vmcnt(5)
	ds_write2_b32 v2, v10, v11 offset1:1
	v_add_u32_e32 v2, 0x848, v26
	ds_write2_b32 v2, v12, v13 offset1:1
	v_add_u32_e32 v2, 0xc60, v26
	s_waitcnt vmcnt(4)
	ds_write2_b32 v2, v14, v15 offset1:1
	v_add_u32_e32 v2, 0xc68, v26
	ds_write2_b32 v2, v16, v17 offset1:1
	v_add_u32_e32 v2, 0x1080, v26
	s_waitcnt vmcnt(3)
	ds_write2_b32 v2, v28, v29 offset1:1
	v_add_u32_e32 v2, 0x1088, v26
	ds_write2_b32 v2, v30, v31 offset1:1
	v_add_u32_e32 v2, 0x14a0, v26
	s_waitcnt vmcnt(2)
	ds_write2_b32 v2, v32, v33 offset1:1
	v_add_u32_e32 v2, 0x14a8, v26
	ds_write2_b32 v2, v34, v35 offset1:1
	v_add_u32_e32 v2, 0x18c0, v26
	s_waitcnt vmcnt(1)
	ds_write2_b32 v2, v36, v37 offset1:1
	v_add_u32_e32 v2, 0x18c8, v26
	ds_write2_b32 v2, v38, v39 offset1:1
	v_add_u32_e32 v2, 0x1ce0, v26
	s_waitcnt vmcnt(0)
	ds_write2_b32 v2, v40, v41 offset1:1
	v_add_u32_e32 v2, 0x1ce8, v26
	ds_write2_b32 v2, v42, v43 offset1:1
	s_waitcnt lgkmcnt(0)
	ds_read2_b32 v[4:5], v0 offset1:33
	s_waitcnt lgkmcnt(0)
	v_cvt_pk_bf16_f32 v6, v4, v5
	ds_read2_b32 v[4:5], v0 offset0:66 offset1:99
	s_waitcnt lgkmcnt(0)
	v_cvt_pk_bf16_f32 v7, v4, v5
	ds_read2_b32 v[4:5], v0 offset0:132 offset1:165
	s_waitcnt lgkmcnt(0)
	v_cvt_pk_bf16_f32 v8, v4, v5
	ds_read2_b32 v[4:5], v0 offset0:198 offset1:231
	s_waitcnt lgkmcnt(0)
	v_cvt_pk_bf16_f32 v9, v4, v5
	v_add_u32_e32 v4, s7, v25
	v_lshl_add_u64 v[2:3], s[12:13], 1, v[20:21]
	v_ashrrev_i32_e32 v5, 31, v4
	v_lshl_add_u64 v[10:11], v[4:5], 1, v[2:3]
	global_store_dwordx4 v[10:11], v[6:9], off nt
	ds_read2_b32 v[6:7], v0 offset0:8 offset1:41
	s_mul_i32 s7, s60, 0x2c000
	s_waitcnt lgkmcnt(0)
	v_cvt_pk_bf16_f32 v6, v6, v7
	ds_read2_b32 v[8:9], v0 offset0:74 offset1:107
	s_waitcnt lgkmcnt(0)
	v_cvt_pk_bf16_f32 v7, v8, v9
	ds_read2_b32 v[8:9], v0 offset0:140 offset1:173
	s_waitcnt lgkmcnt(0)
	v_cvt_pk_bf16_f32 v8, v8, v9
	ds_read2_b32 v[10:11], v0 offset0:206 offset1:239
	s_waitcnt lgkmcnt(0)
	v_cvt_pk_bf16_f32 v9, v10, v11
	v_add_u32_e32 v10, 0xb000, v4
	v_ashrrev_i32_e32 v11, 31, v10
	v_lshl_add_u64 v[10:11], v[10:11], 1, v[2:3]
	global_store_dwordx4 v[10:11], v[6:9], off nt
	ds_read2_b32 v[6:7], v0 offset0:16 offset1:49
	v_add_u32_e32 v25, s7, v25
	s_waitcnt lgkmcnt(0)
	v_cvt_pk_bf16_f32 v6, v6, v7
	ds_read2_b32 v[8:9], v0 offset0:82 offset1:115
	s_waitcnt lgkmcnt(0)
	v_cvt_pk_bf16_f32 v7, v8, v9
	ds_read2_b32 v[8:9], v0 offset0:148 offset1:181
	s_waitcnt lgkmcnt(0)
	v_cvt_pk_bf16_f32 v8, v8, v9
	ds_read2_b32 v[10:11], v0 offset0:214 offset1:247
	s_waitcnt lgkmcnt(0)
	v_cvt_pk_bf16_f32 v9, v10, v11
	v_add_u32_e32 v10, 0x16000, v4
	v_ashrrev_i32_e32 v11, 31, v10
	v_lshl_add_u64 v[10:11], v[10:11], 1, v[2:3]
	global_store_dwordx4 v[10:11], v[6:9], off nt
	ds_read2_b32 v[6:7], v0 offset0:24 offset1:57
	v_add_u32_e32 v4, 0x21000, v4
	s_waitcnt lgkmcnt(0)
	v_cvt_pk_bf16_f32 v6, v6, v7
	ds_read2_b32 v[8:9], v0 offset0:90 offset1:123
	v_ashrrev_i32_e32 v5, 31, v4
	s_waitcnt lgkmcnt(0)
	v_cvt_pk_bf16_f32 v7, v8, v9
	ds_read2_b32 v[8:9], v0 offset0:156 offset1:189
	v_lshl_add_u64 v[2:3], v[4:5], 1, v[2:3]
	s_waitcnt lgkmcnt(0)
	v_cvt_pk_bf16_f32 v8, v8, v9
	ds_read2_b32 v[10:11], v0 offset0:222 offset1:255
	s_waitcnt lgkmcnt(0)
	v_cvt_pk_bf16_f32 v9, v10, v11
	global_store_dwordx4 v[2:3], v[6:9], off nt
	s_waitcnt lgkmcnt(0)
	s_cbranch_scc0 .LBB0_738
